# P4: WG-group stagger at phase start + relaxed vmcnt(24) on the first K-tile after an epilogue so the 16 epilogue stores drain under the next tile's first MFMA blocks
# speedup vs baseline: 1.0132x; 1.0031x over previous
; #define LAS __attribute__((address_space(3)))
; __global__ void __launch_bounds__(NWAVES * 64, 2) mega_fwd(Args args) {
;     ...
;     if (IN(4)) {
;         pg8::Gemm g{F.XN, F.Wup_t, M, FF, D}; pg8::StaticOrder S; S.init(M, FF, F.G, (int)blockIdx.x);
;         LAS float* tab = (LAS float*)(F.lds + UPTAB_OFF);
;         { const int rowi = F.tid & 255;
;           for (int i = F.tid >> 8; i < pg8::UP_TAB_ROUNDS; i += 2) { const int pm = S.pm_at(i); if (pm < 0) break;
;               const f32x4* p = (const f32x4*)(F.stats + (size_t)(pm * 256 + rowi) * 16); const f32x4 a = p[0], b = p[1], c = p[2], d = p[3];
;               const float ssum = ((a[0] + a[1]) + (a[2] + a[3])) + ((b[0] + b[1]) + (b[2] + b[3])) + ((c[0] + c[1]) + (c[2] + c[3])) + ((d[0] + d[1]) + (d[2] + d[3]));
;               tab[i * 256 + rowi] = __builtin_amdgcn_rsqf(ssum * (1.0f / 1024.0f) + EPS); }
;           __syncthreads(); }
;         pg8::EpiUp E{F.H, F.stats, tab};
;         pg8::gemm_phase<pg8::EpiUp, pg8::StaticOrder, PG8_ALIGN, PG8_SP2>(F.lds + RING_OFF, g, S, E);
.LBB0_1367:
	s_or_b64 exec, exec, s[6:7]
	s_cmp_gt_i32 s30, 0
	s_cselect_b64 s[0:1], -1, 0
	s_cmpk_lt_i32 s2, 0xc00
	s_cselect_b64 s[4:5], -1, 0
	s_and_b64 s[0:1], s[4:5], s[0:1]
	v_cndmask_b32_e64 v1, 0, 1, s[0:1]
	v_cmp_ne_u32_e64 s[4:5], 1, v1
	s_andn2_b64 vcc, exec, s[0:1]
	v_readfirstlane_b32 s12, v208
	s_waitcnt lgkmcnt(0)
	s_barrier
	s_mov_b32 s99, 0
	s_lshr_b32 s98, s2, 3
	s_and_b32 s98, s98, 7
	s_cbranch_scc0 .Lstg_p4_done

; #define PG8_STAGE(bufoff, gbase, voff) do { _Pragma("unroll") for (int _i = 0; _i < 2; ++_i) \
;         __builtin_amdgcn_global_load_lds((const unsigned*)((const char*)(gbase) + (voff)[_i]), (PG8_LAS unsigned*)(lds + (bufoff) + ldsw + _i * 8192), 16, 0, 0); } while (0)
; #define PG8_LDA(dst, b, h) do { _Pragma("unroll") for (int m = 0; m < 4; ++m) _Pragma("unroll") for (int k = 0; k < 2; ++k) dst[m][k] = *(const PG8_LAS bf16x8*)(lds + PG8_SA(b, h) + aoff + m * 2048 + k * 1024); } while (0)
; #define PG8_LDB(dst, b, h) do { _Pragma("unroll") for (int n = 0; n < 2; ++n) _Pragma("unroll") for (int k = 0; k < 2; ++k) dst[n][k] = *(const PG8_LAS bf16x8*)(lds + PG8_SB(b, h) + boff + n * 2048 + k * 1024); } while (0)
; #define PG8_MMA(ai, bj, At, Bt) do { __builtin_amdgcn_s_setprio(1); _Pragma("unroll") for (int m = 0; m < 4; ++m) _Pragma("unroll") for (int n = 0; n < 2; ++n) _Pragma("unroll") for (int k = 0; k < 2; ++k) \
;         acc[ai][bj][m][n] = __builtin_amdgcn_mfma_f32_16x16x32_bf16(Bt[n][k], At[m][k], acc[ai][bj][m][n], 0, 0, 0); __builtin_amdgcn_s_setprio(0); } while (0)
; #define PG8_WAIT_V(n) asm volatile("s_waitcnt vmcnt(" #n ")" ::: "memory")
; #define PG8_WAIT_L(n) asm volatile("s_waitcnt lgkmcnt(" #n ")" ::: "memory")
; #define PG8_BAR __builtin_amdgcn_s_barrier()
; #define PG8_SCHED __builtin_amdgcn_sched_barrier(0)
; template <class Epi, class Sched, bool ALIGN_EPI = false, bool SP2 = false>
; __device__ __forceinline__ void gemm_phase(PG8_LAS unsigned char* lds, const Gemm g, const Sched& S, const Epi& E) {
;     ...
;             PG8_LDB(B0, 0, 0); PG8_LDB(B1, 0, 1); PG8_SCHED; PG8_LDA(At, 0, 0); PG8_STAGE(PG8_SA(1, 1), a1 + hstep, voffA);
;             PG8_WAIT_V(8); PG8_WAIT_L(0); PG8_BAR; PG8_MMA(0, 0, At, B0); PG8_MMA(0, 1, At, B1); PG8_BAR; PG8_SCHED;
;             PG8_LDA(At, 0, 1); PG8_STAGE(PG8_SB(0, 0), b2, voffB); PG8_STAGE(PG8_SB(0, 1), b2 + hstep, voffB); PG8_STAGE(PG8_SA(0, 0), a2, voffA);
.LBB0_1380:
	ds_read_b128 v[146:149], v153
	ds_read_b128 v[160:163], v153 offset:1024
	ds_read_b128 v[164:167], v153 offset:2048
	ds_read_b128 v[168:171], v153 offset:3072
	ds_read_b128 v[172:175], v154
	ds_read_b128 v[176:179], v154 offset:1024
	ds_read_b128 v[180:183], v154 offset:2048
	ds_read_b128 v[184:187], v154 offset:3072
	s_add_u32 s0, s4, 0xfffc0080
	s_addc_u32 s1, s5, -1
	s_cmp_eq_u32 s54, 12
	s_cselect_b32 s29, s15, s1
	s_cselect_b32 s28, s25, s0
	s_cselect_b32 s27, s9, s53
	s_cselect_b32 s26, s49, s52
	v_lshl_add_u64 v[222:223], s[4:5], 0, v[140:141]
	s_add_i32 m0, s34, 0xc000
	ds_read_b128 v[188:191], v155
	ds_read_b128 v[192:195], v155 offset:1024
	ds_read_b128 v[196:199], v155 offset:2048
	ds_read_b128 v[200:203], v155 offset:3072
	ds_read_b128 v[204:207], v155 offset:4096
	ds_read_b128 v[210:213], v155 offset:5120
	ds_read_b128 v[214:217], v155 offset:6144
	ds_read_b128 v[218:221], v155 offset:7168
	global_load_lds_dwordx4 v[222:223], off
	v_lshl_add_u64 v[222:223], s[4:5], 0, v[142:143]
	s_add_i32 m0, s34, 0xe000
	s_nop 0
	global_load_lds_dwordx4 v[222:223], off
	s_cmp_eq_u32 s99, 0
	s_cbranch_scc1 .Lrx_p4a_strict
	s_waitcnt vmcnt(24)
	s_branch .Lrx_p4a_done
.Lrx_p4a_strict:
	s_waitcnt vmcnt(8)
.Lrx_p4a_done:
	s_waitcnt lgkmcnt(0)
	s_barrier
	s_setprio 1
	s_waitcnt lgkmcnt(0)
	v_mfma_f32_16x16x32_bf16 v[126:129], v[146:149], v[188:191], v[126:129]
	v_mfma_f32_16x16x32_bf16 v[122:125], v[164:167], v[188:191], v[122:125]
	v_mfma_f32_16x16x32_bf16 v[110:113], v[146:149], v[196:199], v[110:113]
	v_mfma_f32_16x16x32_bf16 v[106:109], v[164:167], v[196:199], v[106:109]
	v_mfma_f32_16x16x32_bf16 v[94:97], v[146:149], v[204:207], v[94:97]
	v_mfma_f32_16x16x32_bf16 v[90:93], v[164:167], v[204:207], v[90:93]
	v_mfma_f32_16x16x32_bf16 v[78:81], v[146:149], v[214:217], v[78:81]
	v_mfma_f32_16x16x32_bf16 v[74:77], v[164:167], v[214:217], v[74:77]
	v_mfma_f32_16x16x32_bf16 v[126:129], v[160:163], v[192:195], v[126:129]
	v_mfma_f32_16x16x32_bf16 v[122:125], v[168:171], v[192:195], v[122:125]
	v_mfma_f32_16x16x32_bf16 v[110:113], v[160:163], v[200:203], v[110:113]
	v_mfma_f32_16x16x32_bf16 v[106:109], v[168:171], v[200:203], v[106:109]
	v_mfma_f32_16x16x32_bf16 v[94:97], v[160:163], v[210:213], v[94:97]
	v_mfma_f32_16x16x32_bf16 v[90:93], v[168:171], v[210:213], v[90:93]
	v_mfma_f32_16x16x32_bf16 v[78:81], v[160:163], v[218:221], v[78:81]
	v_mfma_f32_16x16x32_bf16 v[74:77], v[168:171], v[218:221], v[74:77]
	s_setprio 0
	s_setprio 1
	v_mfma_f32_16x16x32_bf16 v[118:121], v[172:175], v[188:191], v[118:121]
	v_mfma_f32_16x16x32_bf16 v[114:117], v[180:183], v[188:191], v[114:117]
	v_mfma_f32_16x16x32_bf16 v[102:105], v[172:175], v[196:199], v[102:105]
	v_mfma_f32_16x16x32_bf16 v[98:101], v[180:183], v[196:199], v[98:101]
	v_mfma_f32_16x16x32_bf16 v[86:89], v[172:175], v[204:207], v[86:89]
	v_mfma_f32_16x16x32_bf16 v[82:85], v[180:183], v[204:207], v[82:85]
	v_mfma_f32_16x16x32_bf16 v[70:73], v[172:175], v[214:217], v[70:73]
	v_mfma_f32_16x16x32_bf16 v[66:69], v[180:183], v[214:217], v[66:69]
	v_mfma_f32_16x16x32_bf16 v[118:121], v[176:179], v[192:195], v[118:121]
	v_mfma_f32_16x16x32_bf16 v[114:117], v[184:187], v[192:195], v[114:117]
	v_mfma_f32_16x16x32_bf16 v[102:105], v[176:179], v[200:203], v[102:105]
	v_mfma_f32_16x16x32_bf16 v[98:101], v[184:187], v[200:203], v[98:101]
	v_mfma_f32_16x16x32_bf16 v[86:89], v[176:179], v[210:213], v[86:89]
	v_mfma_f32_16x16x32_bf16 v[82:85], v[184:187], v[210:213], v[82:85]
	v_mfma_f32_16x16x32_bf16 v[70:73], v[176:179], v[218:221], v[70:73]
	v_mfma_f32_16x16x32_bf16 v[66:69], v[184:187], v[218:221], v[66:69]
	s_setprio 0
	s_barrier
	s_add_i32 s0, s41, s31
	v_lshl_add_u64 v[222:223], s[26:27], 0, v[132:133]
	s_mov_b32 m0, s0
	ds_read_b128 v[188:191], v155 offset:16384
	ds_read_b128 v[192:195], v155 offset:17408
	ds_read_b128 v[196:199], v155 offset:18432
	ds_read_b128 v[200:203], v155 offset:19456
	ds_read_b128 v[204:207], v155 offset:20480
	ds_read_b128 v[210:213], v155 offset:21504
	ds_read_b128 v[214:217], v155 offset:22528
	ds_read_b128 v[218:221], v155 offset:23552
	global_load_lds_dwordx4 v[222:223], off
	s_add_i32 m0, s0, 0x2000
	s_add_u32 s0, s26, 0x40000
	v_lshl_add_u64 v[224:225], s[26:27], 0, v[136:137]
	s_addc_u32 s1, s27, 0
	s_add_i32 s55, s44, s31
	global_load_lds_dwordx4 v[224:225], off
	v_lshl_add_u64 v[226:227], s[0:1], 0, v[132:133]
	s_mov_b32 m0, s55
	v_lshl_add_u64 v[228:229], s[28:29], 0, v[134:135]
	global_load_lds_dwordx4 v[226:227], off
	v_lshl_add_u64 v[226:227], s[0:1], 0, v[136:137]
	s_add_i32 m0, s55, 0x2000
	s_nop 0
	global_load_lds_dwordx4 v[226:227], off
	v_lshl_add_u64 v[226:227], s[28:29], 0, v[130:131]
	s_mov_b32 m0, s34
	s_nop 0
	global_load_lds_dwordx4 v[226:227], off
	s_mov_b32 m0, s35
	s_nop 0
	global_load_lds_dwordx4 v[228:229], off
	s_cmp_eq_u32 s99, 0
	s_cbranch_scc1 .Lrx_p4b_strict
	s_waitcnt vmcnt(24)
	s_mov_b32 s99, 0
	s_branch .Lrx_p4b_done

; #define PG8_STAGE(bufoff, gbase, voff) do { _Pragma("unroll") for (int _i = 0; _i < 2; ++_i) \
;         __builtin_amdgcn_global_load_lds((const unsigned*)((const char*)(gbase) + (voff)[_i]), (PG8_LAS unsigned*)(lds + (bufoff) + ldsw + _i * 8192), 16, 0, 0); } while (0)
; #define PG8_LDA(dst, b, h) do { _Pragma("unroll") for (int m = 0; m < 4; ++m) _Pragma("unroll") for (int k = 0; k < 2; ++k) dst[m][k] = *(const PG8_LAS bf16x8*)(lds + PG8_SA(b, h) + aoff + m * 2048 + k * 1024); } while (0)
; #define PG8_LDB(dst, b, h) do { _Pragma("unroll") for (int n = 0; n < 2; ++n) _Pragma("unroll") for (int k = 0; k < 2; ++k) dst[n][k] = *(const PG8_LAS bf16x8*)(lds + PG8_SB(b, h) + boff + n * 2048 + k * 1024); } while (0)
; #define PG8_MMA(ai, bj, At, Bt) do { __builtin_amdgcn_s_setprio(1); _Pragma("unroll") for (int m = 0; m < 4; ++m) _Pragma("unroll") for (int n = 0; n < 2; ++n) _Pragma("unroll") for (int k = 0; k < 2; ++k) \
;         acc[ai][bj][m][n] = __builtin_amdgcn_mfma_f32_16x16x32_bf16(Bt[n][k], At[m][k], acc[ai][bj][m][n], 0, 0, 0); __builtin_amdgcn_s_setprio(0); } while (0)
; #define PG8_WAIT_V(n) asm volatile("s_waitcnt vmcnt(" #n ")" ::: "memory")
; #define PG8_WAIT_L(n) asm volatile("s_waitcnt lgkmcnt(" #n ")" ::: "memory")
; #define PG8_BAR __builtin_amdgcn_s_barrier()
; #define PG8_SCHED __builtin_amdgcn_sched_barrier(0)
; template <class Epi, class Sched, bool ALIGN_EPI = false, bool SP2 = false>
; __device__ __forceinline__ void gemm_phase(PG8_LAS unsigned char* lds, const Gemm g, const Sched& S, const Epi& E) {
;     ...
;             PG8_WAIT_V(8); PG8_WAIT_L(0); PG8_BAR; PG8_MMA(0, 0, At, B0); PG8_MMA(0, 1, At, B1); PG8_BAR; PG8_SCHED;
;             PG8_LDA(At, 0, 1); PG8_STAGE(PG8_SB(0, 0), b2, voffB); PG8_STAGE(PG8_SB(0, 1), b2 + hstep, voffB); PG8_STAGE(PG8_SA(0, 0), a2, voffA);
;             PG8_WAIT_V(8); PG8_WAIT_L(0); PG8_BAR; PG8_MMA(1, 0, At, B0); PG8_MMA(1, 1, At, B1); PG8_BAR; PG8_SCHED;
;             PG8_LDB(B0, 1, 0); PG8_LDB(B1, 1, 1); PG8_SCHED; PG8_LDA(At, 1, 0); PG8_STAGE(PG8_SA(0, 1), a2 + hstep, voffA);
;             PG8_WAIT_V(8); PG8_WAIT_L(0); PG8_BAR; PG8_MMA(0, 0, At, B0); PG8_MMA(0, 1, At, B1); PG8_BAR; PG8_SCHED;
.Lrx_p4b_done:
	s_waitcnt lgkmcnt(0)
	s_barrier
	s_setprio 1
	s_waitcnt lgkmcnt(0)
	v_mfma_f32_16x16x32_bf16 v[62:65], v[146:149], v[188:191], v[62:65]
	v_mfma_f32_16x16x32_bf16 v[58:61], v[164:167], v[188:191], v[58:61]
	v_mfma_f32_16x16x32_bf16 v[46:49], v[146:149], v[196:199], v[46:49]
	v_mfma_f32_16x16x32_bf16 v[42:45], v[164:167], v[196:199], v[42:45]
	v_mfma_f32_16x16x32_bf16 v[30:33], v[146:149], v[204:207], v[30:33]
	v_mfma_f32_16x16x32_bf16 v[26:29], v[164:167], v[204:207], v[26:29]
	v_mfma_f32_16x16x32_bf16 v[14:17], v[146:149], v[214:217], v[14:17]
	v_mfma_f32_16x16x32_bf16 v[10:13], v[164:167], v[214:217], v[10:13]
	v_mfma_f32_16x16x32_bf16 v[62:65], v[160:163], v[192:195], v[62:65]
	v_mfma_f32_16x16x32_bf16 v[58:61], v[168:171], v[192:195], v[58:61]
	v_mfma_f32_16x16x32_bf16 v[46:49], v[160:163], v[200:203], v[46:49]
	v_mfma_f32_16x16x32_bf16 v[42:45], v[168:171], v[200:203], v[42:45]
	v_mfma_f32_16x16x32_bf16 v[30:33], v[160:163], v[210:213], v[30:33]
	v_mfma_f32_16x16x32_bf16 v[26:29], v[168:171], v[210:213], v[26:29]
	v_mfma_f32_16x16x32_bf16 v[14:17], v[160:163], v[218:221], v[14:17]
	v_mfma_f32_16x16x32_bf16 v[10:13], v[168:171], v[218:221], v[10:13]
	s_setprio 0
	s_setprio 1
	v_mfma_f32_16x16x32_bf16 v[54:57], v[172:175], v[188:191], v[54:57]
	v_mfma_f32_16x16x32_bf16 v[50:53], v[180:183], v[188:191], v[50:53]
	v_mfma_f32_16x16x32_bf16 v[38:41], v[172:175], v[196:199], v[38:41]
	v_mfma_f32_16x16x32_bf16 v[34:37], v[180:183], v[196:199], v[34:37]
	v_mfma_f32_16x16x32_bf16 v[22:25], v[172:175], v[204:207], v[22:25]
	v_mfma_f32_16x16x32_bf16 v[18:21], v[180:183], v[204:207], v[18:21]
	v_mfma_f32_16x16x32_bf16 v[6:9], v[172:175], v[214:217], v[6:9]
	v_mfma_f32_16x16x32_bf16 v[2:5], v[180:183], v[214:217], v[2:5]
	v_mfma_f32_16x16x32_bf16 v[54:57], v[176:179], v[192:195], v[54:57]
	v_mfma_f32_16x16x32_bf16 v[50:53], v[184:187], v[192:195], v[50:53]
	v_mfma_f32_16x16x32_bf16 v[38:41], v[176:179], v[200:203], v[38:41]
	v_mfma_f32_16x16x32_bf16 v[34:37], v[184:187], v[200:203], v[34:37]
	v_mfma_f32_16x16x32_bf16 v[22:25], v[176:179], v[210:213], v[22:25]
	v_mfma_f32_16x16x32_bf16 v[18:21], v[184:187], v[210:213], v[18:21]
	v_mfma_f32_16x16x32_bf16 v[6:9], v[176:179], v[218:221], v[6:9]
	v_mfma_f32_16x16x32_bf16 v[2:5], v[184:187], v[218:221], v[2:5]
	s_setprio 0
	s_barrier
	ds_read_b128 v[146:149], v157
	ds_read_b128 v[160:163], v157 offset:1024
	ds_read_b128 v[164:167], v157 offset:2048
	ds_read_b128 v[168:171], v157 offset:3072
	ds_read_b128 v[172:175], v158
	ds_read_b128 v[176:179], v158 offset:1024
	ds_read_b128 v[180:183], v158 offset:2048
	ds_read_b128 v[184:187], v158 offset:3072
	s_add_u32 s0, s28, 0x40000
	s_addc_u32 s1, s29, 0
	s_mov_b32 m0, s36
	v_lshl_add_u64 v[230:231], s[0:1], 0, v[130:131]
	ds_read_b128 v[188:191], v155 offset:32768
	ds_read_b128 v[192:195], v155 offset:33792
	ds_read_b128 v[196:199], v155 offset:34816
	ds_read_b128 v[200:203], v155 offset:35840
	ds_read_b128 v[204:207], v155 offset:36864
	ds_read_b128 v[210:213], v155 offset:37888
	ds_read_b128 v[214:217], v155 offset:38912
	ds_read_b128 v[218:221], v155 offset:39936
	global_load_lds_dwordx4 v[230:231], off
	v_lshl_add_u64 v[230:231], s[0:1], 0, v[134:135]
	s_mov_b32 m0, s37
	s_nop 0
	global_load_lds_dwordx4 v[230:231], off
	s_waitcnt vmcnt(8)
	s_waitcnt lgkmcnt(0)
	s_barrier
	s_setprio 1
	s_waitcnt lgkmcnt(0)
	v_mfma_f32_16x16x32_bf16 v[126:129], v[146:149], v[188:191], v[126:129]
	v_mfma_f32_16x16x32_bf16 v[122:125], v[164:167], v[188:191], v[122:125]
	v_mfma_f32_16x16x32_bf16 v[110:113], v[146:149], v[196:199], v[110:113]
	v_mfma_f32_16x16x32_bf16 v[106:109], v[164:167], v[196:199], v[106:109]
	v_mfma_f32_16x16x32_bf16 v[94:97], v[146:149], v[204:207], v[94:97]
	v_mfma_f32_16x16x32_bf16 v[90:93], v[164:167], v[204:207], v[90:93]
	v_mfma_f32_16x16x32_bf16 v[78:81], v[146:149], v[214:217], v[78:81]
	v_mfma_f32_16x16x32_bf16 v[74:77], v[164:167], v[214:217], v[74:77]
	v_mfma_f32_16x16x32_bf16 v[126:129], v[160:163], v[192:195], v[126:129]
	v_mfma_f32_16x16x32_bf16 v[122:125], v[168:171], v[192:195], v[122:125]
	v_mfma_f32_16x16x32_bf16 v[110:113], v[160:163], v[200:203], v[110:113]
	v_mfma_f32_16x16x32_bf16 v[106:109], v[168:171], v[200:203], v[106:109]
	v_mfma_f32_16x16x32_bf16 v[94:97], v[160:163], v[210:213], v[94:97]
	v_mfma_f32_16x16x32_bf16 v[90:93], v[168:171], v[210:213], v[90:93]
	v_mfma_f32_16x16x32_bf16 v[78:81], v[160:163], v[218:221], v[78:81]
	v_mfma_f32_16x16x32_bf16 v[74:77], v[168:171], v[218:221], v[74:77]
	s_setprio 0
	s_setprio 1
	v_mfma_f32_16x16x32_bf16 v[118:121], v[172:175], v[188:191], v[118:121]
	v_mfma_f32_16x16x32_bf16 v[114:117], v[180:183], v[188:191], v[114:117]
	v_mfma_f32_16x16x32_bf16 v[102:105], v[172:175], v[196:199], v[102:105]
	v_mfma_f32_16x16x32_bf16 v[98:101], v[180:183], v[196:199], v[98:101]
	v_mfma_f32_16x16x32_bf16 v[86:89], v[172:175], v[204:207], v[86:89]
	v_mfma_f32_16x16x32_bf16 v[82:85], v[180:183], v[204:207], v[82:85]
	v_mfma_f32_16x16x32_bf16 v[70:73], v[172:175], v[214:217], v[70:73]
	v_mfma_f32_16x16x32_bf16 v[66:69], v[180:183], v[214:217], v[66:69]
	v_mfma_f32_16x16x32_bf16 v[118:121], v[176:179], v[192:195], v[118:121]
	v_mfma_f32_16x16x32_bf16 v[114:117], v[184:187], v[192:195], v[114:117]
	v_mfma_f32_16x16x32_bf16 v[102:105], v[176:179], v[200:203], v[102:105]
	v_mfma_f32_16x16x32_bf16 v[98:101], v[184:187], v[200:203], v[98:101]
	v_mfma_f32_16x16x32_bf16 v[86:89], v[176:179], v[210:213], v[86:89]
	v_mfma_f32_16x16x32_bf16 v[82:85], v[184:187], v[210:213], v[82:85]
	v_mfma_f32_16x16x32_bf16 v[70:73], v[176:179], v[218:221], v[70:73]
	v_mfma_f32_16x16x32_bf16 v[66:69], v[184:187], v[218:221], v[66:69]
	s_setprio 0
	s_barrier
; #define PG8_STAGE(bufoff, gbase, voff) do { _Pragma("unroll") for (int _i = 0; _i < 2; ++_i) \
;         __builtin_amdgcn_global_load_lds((const unsigned*)((const char*)(gbase) + (voff)[_i]), (PG8_LAS unsigned*)(lds + (bufoff) + ldsw + _i * 8192), 16, 0, 0); } while (0)
; #define PG8_LDA(dst, b, h) do { _Pragma("unroll") for (int m = 0; m < 4; ++m) _Pragma("unroll") for (int k = 0; k < 2; ++k) dst[m][k] = *(const PG8_LAS bf16x8*)(lds + PG8_SA(b, h) + aoff + m * 2048 + k * 1024); } while (0)
; #define PG8_MMA(ai, bj, At, Bt) do { __builtin_amdgcn_s_setprio(1); _Pragma("unroll") for (int m = 0; m < 4; ++m) _Pragma("unroll") for (int n = 0; n < 2; ++n) _Pragma("unroll") for (int k = 0; k < 2; ++k) \
;         acc[ai][bj][m][n] = __builtin_amdgcn_mfma_f32_16x16x32_bf16(Bt[n][k], At[m][k], acc[ai][bj][m][n], 0, 0, 0); __builtin_amdgcn_s_setprio(0); } while (0)
; #define PG8_WAIT_V(n) asm volatile("s_waitcnt vmcnt(" #n ")" ::: "memory")
; #define PG8_WAIT_L(n) asm volatile("s_waitcnt lgkmcnt(" #n ")" ::: "memory")
; #define PG8_BAR __builtin_amdgcn_s_barrier()
; #define PG8_SCHED __builtin_amdgcn_sched_barrier(0)
; template <class Epi, class Sched, bool ALIGN_EPI = false, bool SP2 = false>
; __device__ __forceinline__ void gemm_phase(PG8_LAS unsigned char* lds, const Gemm g, const Sched& S, const Epi& E) {
;     ...
;             PG8_LDA(At, 1, 1); PG8_STAGE(PG8_SB(1, 0), b3, voffB); PG8_STAGE(PG8_SB(1, 1), b3 + hstep, voffB); PG8_STAGE(PG8_SA(1, 0), a3, voffA);
;             PG8_WAIT_V(8); PG8_WAIT_L(0); PG8_BAR; PG8_MMA(1, 0, At, B0); PG8_MMA(1, 1, At, B1); PG8_BAR; PG8_SCHED;
;     ...
;         if constexpr (ALIGN_EPI) { if (wr == 0) PG8_BAR; }
	s_add_i32 s0, s45, s31
	v_lshl_add_u64 v[222:223], v[222:223], 0, s[10:11]
	s_mov_b32 m0, s0
	ds_read_b128 v[188:191], v155 offset:49152
	ds_read_b128 v[192:195], v155 offset:50176
	ds_read_b128 v[196:199], v155 offset:51200
	ds_read_b128 v[200:203], v155 offset:52224
	ds_read_b128 v[204:207], v155 offset:53248
	ds_read_b128 v[210:213], v155 offset:54272
	ds_read_b128 v[214:217], v155 offset:55296
	ds_read_b128 v[218:221], v155 offset:56320
	global_load_lds_dwordx4 v[222:223], off
	s_add_i32 m0, s0, 0x2000
	s_add_u32 s0, s26, 0x40080
	v_lshl_add_u64 v[222:223], v[224:225], 0, s[10:11]
	s_addc_u32 s1, s27, 0
	s_add_i32 s26, s46, s31
	global_load_lds_dwordx4 v[222:223], off
	v_lshl_add_u64 v[222:223], s[0:1], 0, v[132:133]
	s_mov_b32 m0, s26
	s_nop 0
	global_load_lds_dwordx4 v[222:223], off
	v_lshl_add_u64 v[222:223], s[0:1], 0, v[136:137]
	s_add_i32 m0, s26, 0x2000
	s_nop 0
	global_load_lds_dwordx4 v[222:223], off
	v_lshl_add_u64 v[222:223], v[226:227], 0, s[10:11]
	s_mov_b32 m0, s38
	s_nop 0
	global_load_lds_dwordx4 v[222:223], off
	v_lshl_add_u64 v[222:223], v[228:229], 0, s[10:11]
	s_mov_b32 m0, s39
	s_nop 0
	global_load_lds_dwordx4 v[222:223], off
	s_waitcnt vmcnt(8)
	s_waitcnt lgkmcnt(0)
	s_barrier
	s_setprio 1
	s_waitcnt lgkmcnt(0)
	v_mfma_f32_16x16x32_bf16 v[62:65], v[146:149], v[188:191], v[62:65]
	v_mfma_f32_16x16x32_bf16 v[58:61], v[164:167], v[188:191], v[58:61]
	v_mfma_f32_16x16x32_bf16 v[46:49], v[146:149], v[196:199], v[46:49]
	v_mfma_f32_16x16x32_bf16 v[42:45], v[164:167], v[196:199], v[42:45]
	v_mfma_f32_16x16x32_bf16 v[30:33], v[146:149], v[204:207], v[30:33]
	v_mfma_f32_16x16x32_bf16 v[26:29], v[164:167], v[204:207], v[26:29]
	v_mfma_f32_16x16x32_bf16 v[14:17], v[146:149], v[214:217], v[14:17]
	v_mfma_f32_16x16x32_bf16 v[10:13], v[164:167], v[214:217], v[10:13]
	v_mfma_f32_16x16x32_bf16 v[62:65], v[160:163], v[192:195], v[62:65]
	v_mfma_f32_16x16x32_bf16 v[58:61], v[168:171], v[192:195], v[58:61]
	v_mfma_f32_16x16x32_bf16 v[46:49], v[160:163], v[200:203], v[46:49]
	v_mfma_f32_16x16x32_bf16 v[42:45], v[168:171], v[200:203], v[42:45]
	v_mfma_f32_16x16x32_bf16 v[30:33], v[160:163], v[210:213], v[30:33]
	v_mfma_f32_16x16x32_bf16 v[26:29], v[168:171], v[210:213], v[26:29]
	v_mfma_f32_16x16x32_bf16 v[14:17], v[160:163], v[218:221], v[14:17]
	v_mfma_f32_16x16x32_bf16 v[10:13], v[168:171], v[218:221], v[10:13]
	s_setprio 0
	s_setprio 1
	v_mfma_f32_16x16x32_bf16 v[54:57], v[172:175], v[188:191], v[54:57]
	v_mfma_f32_16x16x32_bf16 v[50:53], v[180:183], v[188:191], v[50:53]
	v_mfma_f32_16x16x32_bf16 v[38:41], v[172:175], v[196:199], v[38:41]
	v_mfma_f32_16x16x32_bf16 v[34:37], v[180:183], v[196:199], v[34:37]
	v_mfma_f32_16x16x32_bf16 v[22:25], v[172:175], v[204:207], v[22:25]
	v_mfma_f32_16x16x32_bf16 v[18:21], v[180:183], v[204:207], v[18:21]
	v_mfma_f32_16x16x32_bf16 v[6:9], v[172:175], v[214:217], v[6:9]
	v_mfma_f32_16x16x32_bf16 v[2:5], v[180:183], v[214:217], v[2:5]
	v_mfma_f32_16x16x32_bf16 v[54:57], v[176:179], v[192:195], v[54:57]
	v_mfma_f32_16x16x32_bf16 v[50:53], v[184:187], v[192:195], v[50:53]
	v_mfma_f32_16x16x32_bf16 v[38:41], v[176:179], v[200:203], v[38:41]
	v_mfma_f32_16x16x32_bf16 v[34:37], v[184:187], v[200:203], v[34:37]
	v_mfma_f32_16x16x32_bf16 v[22:25], v[176:179], v[210:213], v[22:25]
	v_mfma_f32_16x16x32_bf16 v[18:21], v[184:187], v[210:213], v[18:21]
	v_mfma_f32_16x16x32_bf16 v[6:9], v[176:179], v[218:221], v[6:9]
	v_mfma_f32_16x16x32_bf16 v[2:5], v[184:187], v[218:221], v[2:5]
	s_setprio 0
	s_barrier
	s_add_i32 s54, s54, 2
	s_add_u32 s4, s4, 0x100
	s_addc_u32 s5, s5, 0
	s_add_u32 s52, s52, 0x100
	s_addc_u32 s53, s53, 0
	s_cmp_gt_u32 s54, 13
	s_cbranch_scc0 .LBB0_1380
	s_and_b64 vcc, exec, s[12:13]
	s_cbranch_vccz .LBB0_1383
	s_barrier

; __device__ __forceinline__ unsigned cvt_pk_bf16(float lo, float hi) { unsigned r; asm volatile("v_cvt_pk_bf16_f32 %0, %1, %2" : "=v"(r) : "v"(lo), "v"(hi)); return r; }
;     __device__ __forceinline__ void operator()(const f32x4 (&acc)[2][2][4][2], const Unit& u, int wr, int wc, int fr, int fq) const {
;     ...
;                 for (int bj = 0; bj < 2; ++bj) { f32x4 v0 = acc[ai][bj][m][0] * rstd, v1 = acc[ai][bj][m][1] * rstd;
; #pragma unroll
;                     for (int e = 0; e < 4; ++e) { const float a = fmaxf(v0[e], 0.f), b = fmaxf(v1[e], 0.f); v0[e] = a * a; v1[e] = b * b; }
;                     u32x4 w; w.x = cvt_pk_bf16(v0[0], v0[1]); w.y = cvt_pk_bf16(v0[2], v0[3]); w.z = cvt_pk_bf16(v1[0], v1[1]); w.w = cvt_pk_bf16(v1[2], v1[3]);
;                     __builtin_nontemporal_store(w, (u32x4*)(rowp + bj * HALF)); } }
.LBB0_1415:
	s_waitcnt lgkmcnt(0)
	v_pk_mul_f32 v[10:11], v[10:11], v[18:19] op_sel_hi:[1,0]
	v_pk_mul_f32 v[14:15], v[14:15], v[18:19] op_sel_hi:[1,0]
	v_pk_mul_f32 v[12:13], v[12:13], v[18:19] op_sel_hi:[1,0]
	v_max_f32_e32 v10, 0, v10
	v_lshlrev_b64 v[20:21], 13, v[20:21]
	v_pk_mul_f32 v[16:17], v[16:17], v[18:19] op_sel_hi:[1,0]
	v_mul_f32_e32 v19, v10, v10
	v_max_f32_e32 v10, 0, v15
	v_max_f32_e32 v11, 0, v11
	v_max_f32_e32 v12, 0, v12
	v_lshl_add_u64 v[20:21], s[50:51], 0, v[20:21]
	v_max_f32_e32 v14, 0, v14
	v_mul_f32_e32 v10, v10, v10
	v_mul_f32_e32 v15, v11, v11
	v_max_f32_e32 v11, 0, v16
	v_mul_f32_e32 v16, v12, v12
	v_max_f32_e32 v12, 0, v17
	v_max_f32_e32 v13, 0, v13
	v_pk_mul_f32 v[4:5], v[4:5], v[18:19] op_sel_hi:[1,0]
	v_pk_mul_f32 v[2:3], v[2:3], v[18:19] op_sel_hi:[1,0]
	v_lshl_add_u64 v[20:21], v[148:149], 1, v[20:21]
	v_mul_f32_e32 v14, v14, v14
	v_mul_f32_e32 v11, v11, v11
	v_mul_f32_e32 v12, v12, v12
	v_mul_f32_e32 v13, v13, v13
	v_cvt_pk_bf16_f32 v10, v14, v10
	v_pk_mul_f32 v[8:9], v[8:9], v[18:19] op_sel_hi:[1,0]
	v_pk_mul_f32 v[6:7], v[6:7], v[18:19] op_sel_hi:[1,0]
	v_max_f32_e32 v2, 0, v2
	v_max_f32_e32 v3, 0, v3
	v_max_f32_e32 v4, 0, v4
	v_cvt_pk_bf16_f32 v11, v11, v12
	v_cvt_pk_bf16_f32 v12, v19, v15
	v_cvt_pk_bf16_f32 v13, v16, v13
	global_store_dwordx4 v[20:21], v[10:13], off nt
	v_max_f32_e32 v5, 0, v5
	v_max_f32_e32 v6, 0, v6
	v_mul_f32_e32 v10, v2, v2
	v_max_f32_e32 v2, 0, v7
	v_mul_f32_e32 v7, v3, v3
	v_max_f32_e32 v3, 0, v8
	v_mul_f32_e32 v8, v4, v4
	v_max_f32_e32 v4, 0, v9
	v_mul_f32_e32 v2, v2, v2
	v_mul_f32_e32 v3, v3, v3
	v_mul_f32_e32 v4, v4, v4
	v_mul_f32_e32 v5, v5, v5
	s_andn2_b64 vcc, exec, s[16:17]
	s_mov_b64 s[4:5], -1
	v_mul_f32_e32 v6, v6, v6
	v_cvt_pk_bf16_f32 v2, v6, v2
	v_cvt_pk_bf16_f32 v3, v3, v4
	v_cvt_pk_bf16_f32 v4, v10, v7
	v_cvt_pk_bf16_f32 v5, v8, v5
	global_store_dwordx4 v[20:21], v[2:5], off offset:256 nt
	s_mov_b32 s99, 1
	s_cbranch_vccnz .LBB0_1375
	s_andn2_b64 vcc, exec, s[6:7]
	s_cbranch_vccnz .LBB0_1374
	s_barrier
	s_branch .LBB0_1374
